# GEMM: rstd row scales for in-proj/FF1 epilogues prefetched at tile start; epilogue no longer drains vmcnt
# baseline (speedup 1.0000x reference)
; __device__ __forceinline__ unsigned pk2(float lo, float hi) { const f32x2_t f = {lo, hi}; const bf16x2_t b = __builtin_convertvector(f, bf16x2_t); return __builtin_bit_cast(unsigned, b); }
;   __device__ bool next(int i, Unit& u) const {
;     const long L = (long)i * G + c; if (L >= nwg) return false;
;     int wgid = (int)L; { const int q = nwg / NXCD, r = nwg % NXCD, xcd = wgid % NXCD, off = wgid / NXCD; wgid = (xcd < r ? xcd * (q + 1) : r * (q + 1) + (xcd - r) * q) + off; }
;     const int nig = WGM * nN, gid = wgid / nig, fm = gid * WGM, gsz = (nM - fm) < WGM ? (nM - fm) : WGM;
;     u.pm = fm + ((wgid % nig) % gsz); u.pn = (wgid % nig) / gsz; u.swap = (u.pn >= slo && u.pn < shi) ? 1 : 0; return true;
;   __device__ __forceinline__ void operator()(const f32x4 (&acc)[2][2][4][2], const pg8::Unit& u, int wr, int wc, int fr, int fq) const {
;     ...
;       const float* rstd1 = (const float*)(ws + O_RSTD1) + (size_t)slice * TS;
;       if (u.swap) {
;         u16* hyT = (u16*)(ws + O_HYT);
;         f32x4 rr[2][2];
; #pragma unroll
;         for (int bj = 0; bj < 2; ++bj) { rr[bj][0] = *(const f32x4*)(rstd1 + col0 + bj * 128); rr[bj][1] = *(const f32x4*)(rstd1 + col0 + bj * 128 + 4); }
;         __builtin_amdgcn_sched_barrier(0);
; #pragma unroll
;         for (int bj = 0; bj < 2; ++bj) {
;           const int tok0 = col0 + bj * 128;
; #pragma unroll
;           for (int ai = 0; ai < 2; ++ai)
; #pragma unroll
;             for (int m = 0; m < 4; ++m) {
;               const int ch = row0 + ai * 128 + m * 16 - 4608;
;               const f32x4 a = acc[ai][bj][m][0] * rr[bj][0], b = acc[ai][bj][m][1] * rr[bj][1];
;               u32x4 o; o.x = pk2(a[0], a[1]); o.y = pk2(a[2], a[3]); o.z = pk2(b[0], b[1]); o.w = pk2(b[2], b[3]);
;               *(u32x4*)(hyT + (size_t)ch * TS + tok0) = o;
;             }
;         }
;       } else {
;         u16* qkv = (u16*)(ws + O_QKV); u16* sg = (u16*)(ws + O_SG + (size_t)(slice & 1) * SG_BYTES);
;         const bool isg = (u.pn >= 30);
;         float rsv[2][4];
; #pragma unroll
;         for (int ai = 0; ai < 2; ++ai)
; #pragma unroll
;           for (int m = 0; m < 4; ++m) rsv[ai][m] = rstd1[row0 + ai * 128 + m * 16];
.LBB0_51:
	s_add_i32 s68, s68, 1
	v_readlane_b32 s0, v253, 15
	v_readlane_b32 s8, v253, 6
	s_mul_i32 s0, s68, s0
	s_mul_hi_u32 s1, s68, s8
	s_add_i32 s1, s1, s0
	s_mul_i32 s0, s68, s8
	v_readlane_b32 s8, v253, 9
	s_mov_b64 s[12:13], s[16:17]
	s_add_u32 s16, s0, s8
	v_readlane_b32 s0, v253, 13
	s_addc_u32 s17, s1, s0
	v_mov_b64_e32 v[0:1], s[92:93]
	v_cmp_ge_i64_e64 s[8:9], s[16:17], v[0:1]
	s_mov_b64 s[10:11], s[18:19]
	s_mov_b32 s73, s87
	s_mov_b32 s72, s86
	s_mov_b32 s71, s24
	s_cmp_eq_u32 s98, 5
	s_cbranch_scc1 .Lpf_ff1
	s_cmp_eq_u32 s98, 1
	s_cbranch_scc0 .Lpf_skip
	s_cmp_eq_u32 s71, 0
	s_cbranch_scc0 .Lpf_swap
	s_lshl_b32 vcc_lo, s73, 8
	s_add_i32 vcc_lo, vcc_lo, s28
	v_or_b32_e32 v252, vcc_lo, v186
	v_lshlrev_b32_e32 v252, 2, v252
	global_load_dword v238, v252, s[82:83]
	global_load_dword v239, v252, s[82:83] offset:64
	global_load_dword v240, v252, s[82:83] offset:128
	global_load_dword v241, v252, s[82:83] offset:192
	global_load_dword v244, v252, s[82:83] offset:512
	global_load_dword v245, v252, s[82:83] offset:576
	global_load_dword v246, v252, s[82:83] offset:640
	global_load_dword v247, v252, s[82:83] offset:704
	s_branch .Lpf_skip
.Lpf_swap:
	v_lshl_or_b32 v252, s73, 8, v188
	v_lshlrev_b32_e32 v252, 2, v252
	global_load_dwordx4 v[238:241], v252, s[82:83]
	global_load_dwordx4 v[244:247], v252, s[82:83] offset:16
	global_load_dwordx4 v[248:251], v252, s[82:83] offset:512
	global_load_dwordx2 v[230:231], v252, s[82:83] offset:528
	global_load_dwordx2 v[234:235], v252, s[82:83] offset:536
	s_branch .Lpf_skip
.Lpf_ff1:
	s_lshl_b32 vcc_lo, s73, 8
	s_add_i32 vcc_lo, vcc_lo, s28
	v_or_b32_e32 v252, vcc_lo, v186
	v_lshlrev_b32_e32 v252, 2, v252
	v_readlane_b32 vcc_lo, v254, 16
	v_readlane_b32 vcc_hi, v254, 17
	s_nop 4
	global_load_dword v238, v252, vcc
	global_load_dword v239, v252, vcc offset:64
	global_load_dword v240, v252, vcc offset:128
	global_load_dword v241, v252, vcc offset:192
	global_load_dword v244, v252, vcc offset:512
	global_load_dword v245, v252, vcc offset:576
	global_load_dword v246, v252, vcc offset:640
	global_load_dword v247, v252, vcc offset:704
.Lpf_skip:
	v_cmp_lt_i64_e64 s[0:1], s[16:17], v[0:1]
	s_and_b64 vcc, exec, s[8:9]
	s_cbranch_vccnz .LBB0_53
	s_ashr_i32 s17, s16, 31
	s_lshr_b32 s17, s17, 29
	s_add_i32 s17, s16, s17
	s_ashr_i32 s18, s17, 3
	s_and_b32 s17, s17, -8
	s_sub_i32 s16, s16, s17
	s_lshr_b32 s17, s16, 31
	s_or_b32 s17, s81, s17
	s_mul_i32 s16, s17, s16
	s_add_i32 s16, s16, s18
	s_abs_i32 s18, s16
	s_mul_hi_u32 s19, s18, s70
	s_mul_i32 s24, s19, s3
	s_ashr_i32 s17, s16, 31
	s_sub_i32 s18, s18, s24
	s_xor_b32 s17, s17, s69
	s_add_i32 s24, s19, 1
	s_sub_i32 s74, s18, s3
	s_cmp_ge_u32 s18, s3
	s_cselect_b32 s19, s24, s19
	s_cselect_b32 s18, s74, s18
	s_add_i32 s24, s19, 1
	s_cmp_ge_u32 s18, s3
	s_cselect_b32 s18, s24, s19
	s_xor_b32 s18, s18, s17
	s_sub_i32 s17, s18, s17
	s_lshl_b32 s18, s17, 3
	s_sub_i32 s19, s79, s18
	s_min_i32 s19, s19, 8
	s_abs_i32 s24, s19
	v_cvt_f32_u32_e32 v0, s24
	s_sub_i32 s75, 0, s24
	s_mul_i32 s17, s17, s80
	s_sub_i32 s16, s16, s17
	v_rcp_iflag_f32_e32 v0, v0
	s_abs_i32 s74, s16
	s_xor_b32 s17, s16, s19
	s_ashr_i32 s17, s17, 31
	v_mul_f32_e32 v0, 0x4f7ffffe, v0
	v_cvt_u32_f32_e32 v0, v0
	s_nop 0
	v_readfirstlane_b32 s76, v0
	s_mul_i32 s75, s75, s76
	s_mul_hi_u32 s75, s76, s75
	s_add_i32 s76, s76, s75
	s_mul_hi_u32 s75, s74, s76
	s_mul_i32 s76, s75, s24
	s_sub_i32 s74, s74, s76
	s_add_i32 s76, s75, 1
	s_sub_i32 s77, s74, s24
	s_cmp_ge_u32 s74, s24
	s_cselect_b32 s75, s76, s75
	s_cselect_b32 s74, s77, s74
	s_add_i32 s76, s75, 1
	s_cmp_ge_u32 s74, s24
	s_cselect_b32 s24, s76, s75
	s_xor_b32 s24, s24, s17
	s_sub_i32 s86, s24, s17
	s_mul_i32 s17, s86, s19
	s_sub_i32 s16, s16, s17
	s_add_i32 s87, s16, s18
	v_readlane_b32 s16, v254, 37
	s_cmp_ge_i32 s86, s16
	v_readlane_b32 s18, v254, 35
	s_cselect_b64 s[16:17], -1, 0
	s_cmp_lt_i32 s86, s18
	s_cselect_b64 s[18:19], -1, 0
	s_and_b64 s[16:17], s[16:17], s[18:19]
	v_cndmask_b32_e64 v0, 0, 1, s[16:17]
	s_nop 0
	v_readfirstlane_b32 s24, v0

; __device__ __forceinline__ unsigned pk2(float lo, float hi) { const f32x2_t f = {lo, hi}; const bf16x2_t b = __builtin_convertvector(f, bf16x2_t); return __builtin_bit_cast(unsigned, b); }
;   __device__ __forceinline__ void operator()(const f32x4 (&acc)[2][2][4][2], const pg8::Unit& u, int wr, int wc, int fr, int fq) const {
;     ...
;       const float* rs2 = (const float*)(ws + O_RSTD2) + (size_t)slice * TS; u16* hb = (u16*)(ws + O_HB + (size_t)(slice & 1) * HB_BYTES);
;       float rsv[2][4];
; #pragma unroll
;       for (int ai = 0; ai < 2; ++ai)
; #pragma unroll
;         for (int m = 0; m < 4; ++m) rsv[ai][m] = rs2[row0 + ai * 128 + m * 16];
;       __builtin_amdgcn_sched_barrier(0);
; #pragma unroll
;       for (int ai = 0; ai < 2; ++ai)
; #pragma unroll
;         for (int m = 0; m < 4; ++m) {
;           const int row = row0 + ai * 128 + m * 16; const float rs = rsv[ai][m];
; #pragma unroll
;           for (int bj = 0; bj < 2; ++bj) {
;             const int c = col0 + bj * 128;
;             f32x4 a = acc[ai][bj][m][0] * rs, b = acc[ai][bj][m][1] * rs;
; #pragma unroll
;             for (int e = 0; e < 4; ++e) { a[e] = fmaxf(a[e], 0.f); a[e] *= a[e]; b[e] = fmaxf(b[e], 0.f); b[e] *= b[e]; }
;             u32x4 o; o.x = pk2(a[0], a[1]); o.y = pk2(a[2], a[3]); o.z = pk2(b[0], b[1]); o.w = pk2(b[2], b[3]);
;             *(u32x4*)(hb + (size_t)row * DFF + c) = o;
;           }
;         }
.LBB0_62:
	s_andn2_b64 vcc, exec, s[10:11]
	s_cbranch_vccnz .LBB0_64
	v_readlane_b32 s10, v254, 16
	v_ashrrev_i32_e32 v177, 31, v176
	v_readlane_b32 s11, v254, 17
	v_or_b32_e32 v150, 16, v176
	v_or_b32_e32 v152, 32, v176
	v_lshl_add_u64 v[130:131], v[176:177], 2, s[10:11]
	v_mov_b32_e32 v144, v238
	v_mov_b32_e32 v146, v239
	v_mov_b32_e32 v148, v240
	v_mov_b32_e32 v138, v241
	v_mov_b32_e32 v136, v244
	v_mov_b32_e32 v134, v245
	v_mov_b32_e32 v132, v246
	v_mov_b32_e32 v80, v247
	v_or_b32_e32 v154, 48, v176
	v_ashrrev_i32_e32 v151, 31, v150
	v_ashrrev_i32_e32 v153, 31, v152
	v_ashrrev_i32_e32 v155, 31, v154
	v_pk_mul_f32 v[142:143], v[126:127], v[144:145] op_sel_hi:[1,0]
	v_pk_mul_f32 v[156:157], v[124:125], v[144:145] op_sel_hi:[1,0]
	v_readlane_b32 s10, v254, 23
	v_pk_mul_f32 v[140:141], v[128:129], v[144:145] op_sel_hi:[1,0]
	v_pk_mul_f32 v[158:159], v[122:123], v[144:145] op_sel_hi:[1,0]
	v_max_f32_e32 v142, 0, v142
	v_max_f32_e32 v143, 0, v143
	v_max_f32_e32 v156, 0, v156
	v_max_f32_e32 v157, 0, v157
	v_lshlrev_b64 v[130:131], 13, v[176:177]
	v_readlane_b32 s11, v254, 24
	v_max_f32_e32 v158, 0, v158
	v_pk_mul_f32 v[142:143], v[142:143], v[142:143]
	v_max_f32_e32 v159, 0, v159
	v_max_f32_e32 v140, 0, v140
	v_max_f32_e32 v141, 0, v141
	v_pk_mul_f32 v[156:157], v[156:157], v[156:157]
	v_ashrrev_i32_e32 v175, 31, v174
	v_lshl_add_u64 v[130:131], s[10:11], 0, v[130:131]
	v_pk_mul_f32 v[158:159], v[158:159], v[158:159]
	v_pk_mul_f32 v[160:161], v[140:141], v[140:141]
	v_cvt_pk_bf16_f32 v140, v142, v143
	v_cvt_pk_bf16_f32 v143, v156, v157
	v_lshlrev_b64 v[156:157], 1, v[174:175]
	v_cvt_pk_bf16_f32 v141, v160, v161
	v_cvt_pk_bf16_f32 v142, v158, v159
	v_lshl_add_u64 v[130:131], v[130:131], 0, v[156:157]
	flat_store_dwordx4 v[130:131], v[140:143]
	v_pk_mul_f32 v[158:159], v[58:59], v[144:145] op_sel_hi:[1,0]
	s_nop 0
	v_pk_mul_f32 v[140:141], v[62:63], v[144:145] op_sel_hi:[1,0]
	v_pk_mul_f32 v[142:143], v[60:61], v[144:145] op_sel_hi:[1,0]
	v_pk_mul_f32 v[144:145], v[56:57], v[144:145] op_sel_hi:[1,0]
	v_max_f32_e32 v142, 0, v142
	v_max_f32_e32 v144, 0, v144
	v_max_f32_e32 v143, 0, v143
	v_max_f32_e32 v145, 0, v145
	v_max_f32_e32 v140, 0, v140
	v_max_f32_e32 v158, 0, v158
	v_max_f32_e32 v141, 0, v141
	v_max_f32_e32 v159, 0, v159
	v_pk_mul_f32 v[142:143], v[142:143], v[142:143]
	v_pk_mul_f32 v[144:145], v[144:145], v[144:145]
	v_pk_mul_f32 v[160:161], v[140:141], v[140:141]
	v_pk_mul_f32 v[158:159], v[158:159], v[158:159]
	v_cvt_pk_bf16_f32 v140, v142, v143
	v_cvt_pk_bf16_f32 v141, v160, v161
	v_cvt_pk_bf16_f32 v142, v144, v145
	v_cvt_pk_bf16_f32 v143, v158, v159
	flat_store_dwordx4 v[130:131], v[140:143] offset:256
	v_pk_mul_f32 v[158:159], v[114:115], v[146:147] op_sel_hi:[1,0]
	s_nop 0
	v_lshlrev_b64 v[140:141], 13, v[150:151]
	v_lshl_add_u64 v[144:145], s[10:11], 0, v[140:141]
	v_pk_mul_f32 v[140:141], v[120:121], v[146:147] op_sel_hi:[1,0]
	v_pk_mul_f32 v[142:143], v[118:119], v[146:147] op_sel_hi:[1,0]
	v_pk_mul_f32 v[150:151], v[116:117], v[146:147] op_sel_hi:[1,0]
	v_max_f32_e32 v142, 0, v142
	v_max_f32_e32 v158, 0, v158
	v_max_f32_e32 v143, 0, v143
	v_max_f32_e32 v159, 0, v159
	v_max_f32_e32 v140, 0, v140
	v_max_f32_e32 v150, 0, v150
	v_max_f32_e32 v141, 0, v141
	v_max_f32_e32 v151, 0, v151
	v_pk_mul_f32 v[142:143], v[142:143], v[142:143]
	v_pk_mul_f32 v[158:159], v[158:159], v[158:159]
	v_pk_mul_f32 v[160:161], v[140:141], v[140:141]
	v_pk_mul_f32 v[150:151], v[150:151], v[150:151]
	v_cvt_pk_bf16_f32 v140, v142, v143
	v_cvt_pk_bf16_f32 v141, v160, v161
	v_cvt_pk_bf16_f32 v142, v158, v159
	v_cvt_pk_bf16_f32 v143, v150, v151
	v_lshl_add_u64 v[144:145], v[144:145], 0, v[156:157]
	flat_store_dwordx4 v[144:145], v[140:143]
	v_pk_mul_f32 v[150:151], v[50:51], v[146:147] op_sel_hi:[1,0]
	s_nop 0
	v_pk_mul_f32 v[140:141], v[54:55], v[146:147] op_sel_hi:[1,0]
	v_pk_mul_f32 v[142:143], v[52:53], v[146:147] op_sel_hi:[1,0]
	v_pk_mul_f32 v[146:147], v[48:49], v[146:147] op_sel_hi:[1,0]
	v_max_f32_e32 v142, 0, v142
	v_max_f32_e32 v146, 0, v146
	v_max_f32_e32 v143, 0, v143
	v_max_f32_e32 v147, 0, v147
	v_max_f32_e32 v140, 0, v140
	v_max_f32_e32 v150, 0, v150
	v_max_f32_e32 v141, 0, v141
	v_max_f32_e32 v151, 0, v151
	v_pk_mul_f32 v[142:143], v[142:143], v[142:143]
	v_pk_mul_f32 v[146:147], v[146:147], v[146:147]
	v_pk_mul_f32 v[158:159], v[140:141], v[140:141]
	v_pk_mul_f32 v[150:151], v[150:151], v[150:151]
	v_cvt_pk_bf16_f32 v140, v142, v143
	v_cvt_pk_bf16_f32 v141, v158, v159
	v_cvt_pk_bf16_f32 v142, v146, v147
	v_cvt_pk_bf16_f32 v143, v150, v151
	flat_store_dwordx4 v[144:145], v[140:143] offset:256
	v_pk_mul_f32 v[146:147], v[108:109], v[148:149] op_sel_hi:[1,0]
	v_pk_mul_f32 v[150:151], v[106:107], v[148:149] op_sel_hi:[1,0]
	v_lshlrev_b64 v[140:141], 13, v[152:153]
	v_lshl_add_u64 v[144:145], s[10:11], 0, v[140:141]
	v_pk_mul_f32 v[140:141], v[112:113], v[148:149] op_sel_hi:[1,0]
	v_pk_mul_f32 v[142:143], v[110:111], v[148:149] op_sel_hi:[1,0]
	v_max_f32_e32 v150, 0, v150
	v_max_f32_e32 v142, 0, v142
	v_max_f32_e32 v143, 0, v143
	v_max_f32_e32 v151, 0, v151
	v_max_f32_e32 v140, 0, v140
	v_max_f32_e32 v146, 0, v146
	v_max_f32_e32 v141, 0, v141
	v_max_f32_e32 v147, 0, v147
	v_pk_mul_f32 v[142:143], v[142:143], v[142:143]
	v_pk_mul_f32 v[150:151], v[150:151], v[150:151]
	v_pk_mul_f32 v[152:153], v[140:141], v[140:141]
	v_pk_mul_f32 v[146:147], v[146:147], v[146:147]
	v_cvt_pk_bf16_f32 v140, v142, v143
	v_cvt_pk_bf16_f32 v141, v152, v153
	v_cvt_pk_bf16_f32 v142, v150, v151
	v_cvt_pk_bf16_f32 v143, v146, v147
	v_lshl_add_u64 v[144:145], v[144:145], 0, v[156:157]
	flat_store_dwordx4 v[144:145], v[140:143]
	v_pk_mul_f32 v[146:147], v[42:43], v[148:149] op_sel_hi:[1,0]
; __device__ __forceinline__ unsigned pk2(float lo, float hi) { const f32x2_t f = {lo, hi}; const bf16x2_t b = __builtin_convertvector(f, bf16x2_t); return __builtin_bit_cast(unsigned, b); }
;   __device__ __forceinline__ void operator()(const f32x4 (&acc)[2][2][4][2], const pg8::Unit& u, int wr, int wc, int fr, int fq) const {
;     ...
; #pragma unroll
;       for (int ai = 0; ai < 2; ++ai)
; #pragma unroll
;         for (int m = 0; m < 4; ++m) {
;           const int row = row0 + ai * 128 + m * 16; const float rs = rsv[ai][m];
; #pragma unroll
;           for (int bj = 0; bj < 2; ++bj) {
;             const int c = col0 + bj * 128;
;             f32x4 a = acc[ai][bj][m][0] * rs, b = acc[ai][bj][m][1] * rs;
; #pragma unroll
;             for (int e = 0; e < 4; ++e) { a[e] = fmaxf(a[e], 0.f); a[e] *= a[e]; b[e] = fmaxf(b[e], 0.f); b[e] *= b[e]; }
;             u32x4 o; o.x = pk2(a[0], a[1]); o.y = pk2(a[2], a[3]); o.z = pk2(b[0], b[1]); o.w = pk2(b[2], b[3]);
;             *(u32x4*)(hb + (size_t)row * DFF + c) = o;
;           }
;         }
	s_nop 0
	v_pk_mul_f32 v[140:141], v[46:47], v[148:149] op_sel_hi:[1,0]
	v_pk_mul_f32 v[142:143], v[44:45], v[148:149] op_sel_hi:[1,0]
	v_pk_mul_f32 v[148:149], v[40:41], v[148:149] op_sel_hi:[1,0]
	v_max_f32_e32 v142, 0, v142
	v_max_f32_e32 v148, 0, v148
	v_max_f32_e32 v143, 0, v143
	v_max_f32_e32 v149, 0, v149
	v_max_f32_e32 v140, 0, v140
	v_max_f32_e32 v146, 0, v146
	v_max_f32_e32 v141, 0, v141
	v_max_f32_e32 v147, 0, v147
	v_pk_mul_f32 v[142:143], v[142:143], v[142:143]
	v_pk_mul_f32 v[148:149], v[148:149], v[148:149]
	v_pk_mul_f32 v[150:151], v[140:141], v[140:141]
	v_pk_mul_f32 v[146:147], v[146:147], v[146:147]
	v_cvt_pk_bf16_f32 v140, v142, v143
	v_cvt_pk_bf16_f32 v141, v150, v151
	v_cvt_pk_bf16_f32 v142, v148, v149
	v_cvt_pk_bf16_f32 v143, v146, v147
	flat_store_dwordx4 v[144:145], v[140:143] offset:256
	v_pk_mul_f32 v[146:147], v[100:101], v[138:139] op_sel_hi:[1,0]
	v_pk_mul_f32 v[148:149], v[98:99], v[138:139] op_sel_hi:[1,0]
	v_lshlrev_b64 v[140:141], 13, v[154:155]
	v_lshl_add_u64 v[144:145], s[10:11], 0, v[140:141]
	v_pk_mul_f32 v[140:141], v[104:105], v[138:139] op_sel_hi:[1,0]
	v_pk_mul_f32 v[142:143], v[102:103], v[138:139] op_sel_hi:[1,0]
	v_max_f32_e32 v148, 0, v148
	v_max_f32_e32 v142, 0, v142
	v_max_f32_e32 v143, 0, v143
	v_max_f32_e32 v149, 0, v149
	v_max_f32_e32 v140, 0, v140
	v_max_f32_e32 v146, 0, v146
	v_max_f32_e32 v141, 0, v141
	v_max_f32_e32 v147, 0, v147
	v_pk_mul_f32 v[142:143], v[142:143], v[142:143]
	v_pk_mul_f32 v[148:149], v[148:149], v[148:149]
	v_pk_mul_f32 v[150:151], v[140:141], v[140:141]
	v_pk_mul_f32 v[146:147], v[146:147], v[146:147]
	v_cvt_pk_bf16_f32 v140, v142, v143
	v_cvt_pk_bf16_f32 v141, v150, v151
	v_cvt_pk_bf16_f32 v142, v148, v149
	v_cvt_pk_bf16_f32 v143, v146, v147
	v_lshl_add_u64 v[144:145], v[144:145], 0, v[156:157]
	flat_store_dwordx4 v[144:145], v[140:143]
	v_pk_mul_f32 v[146:147], v[34:35], v[138:139] op_sel_hi:[1,0]
	s_mov_b64 s[10:11], 0x100000
	v_pk_mul_f32 v[140:141], v[38:39], v[138:139] op_sel_hi:[1,0]
	v_pk_mul_f32 v[142:143], v[36:37], v[138:139] op_sel_hi:[1,0]
	v_pk_mul_f32 v[138:139], v[32:33], v[138:139] op_sel_hi:[1,0]
	v_max_f32_e32 v142, 0, v142
	v_max_f32_e32 v138, 0, v138
	v_max_f32_e32 v139, 0, v139
	v_max_f32_e32 v143, 0, v143
	v_pk_mul_f32 v[148:149], v[138:139], v[138:139]
	v_max_f32_e32 v138, 0, v140
	v_max_f32_e32 v140, 0, v146
	v_max_f32_e32 v139, 0, v141
	v_max_f32_e32 v141, 0, v147
	v_pk_mul_f32 v[142:143], v[142:143], v[142:143]
	v_pk_mul_f32 v[150:151], v[138:139], v[138:139]
	v_pk_mul_f32 v[146:147], v[140:141], v[140:141]
	v_cvt_pk_bf16_f32 v138, v142, v143
	v_cvt_pk_bf16_f32 v139, v150, v151
	v_cvt_pk_bf16_f32 v140, v148, v149
	v_cvt_pk_bf16_f32 v141, v146, v147
	flat_store_dwordx4 v[144:145], v[138:141] offset:256
	v_pk_mul_f32 v[142:143], v[92:93], v[136:137] op_sel_hi:[1,0]
	v_pk_mul_f32 v[144:145], v[90:91], v[136:137] op_sel_hi:[1,0]
	v_pk_mul_f32 v[140:141], v[94:95], v[136:137] op_sel_hi:[1,0]
	v_pk_mul_f32 v[138:139], v[96:97], v[136:137] op_sel_hi:[1,0]
	v_max_f32_e32 v140, 0, v140
	v_max_f32_e32 v141, 0, v141
	v_max_f32_e32 v142, 0, v142
	v_max_f32_e32 v143, 0, v143
	v_max_f32_e32 v144, 0, v144
	v_pk_mul_f32 v[140:141], v[140:141], v[140:141]
	v_max_f32_e32 v145, 0, v145
	v_max_f32_e32 v138, 0, v138
	v_max_f32_e32 v139, 0, v139
	v_pk_mul_f32 v[142:143], v[142:143], v[142:143]
	v_pk_mul_f32 v[144:145], v[144:145], v[144:145]
	v_pk_mul_f32 v[146:147], v[138:139], v[138:139]
	v_cvt_pk_bf16_f32 v138, v140, v141
	v_cvt_pk_bf16_f32 v141, v142, v143
	v_lshl_add_u64 v[142:143], v[130:131], 0, s[10:11]
	s_mov_b32 s10, 0x100000
	v_cvt_pk_bf16_f32 v140, v144, v145
	v_add_co_u32_e32 v144, vcc, s10, v130
	v_cvt_pk_bf16_f32 v139, v146, v147
	s_nop 0
	v_addc_co_u32_e32 v145, vcc, 0, v131, vcc
	flat_store_dwordx4 v[144:145], v[138:141]
	v_pk_mul_f32 v[144:145], v[26:27], v[136:137] op_sel_hi:[1,0]
	s_mov_b64 s[10:11], 0x120000
	v_pk_mul_f32 v[138:139], v[30:31], v[136:137] op_sel_hi:[1,0]
	v_pk_mul_f32 v[140:141], v[28:29], v[136:137] op_sel_hi:[1,0]
	v_pk_mul_f32 v[136:137], v[24:25], v[136:137] op_sel_hi:[1,0]
	v_max_f32_e32 v140, 0, v140
	v_max_f32_e32 v136, 0, v136
	v_max_f32_e32 v137, 0, v137
	v_max_f32_e32 v141, 0, v141
	v_pk_mul_f32 v[146:147], v[136:137], v[136:137]
	v_max_f32_e32 v136, 0, v138
	v_max_f32_e32 v138, 0, v144
	v_max_f32_e32 v137, 0, v139
	v_max_f32_e32 v139, 0, v145
	v_pk_mul_f32 v[140:141], v[140:141], v[140:141]
	v_pk_mul_f32 v[148:149], v[136:137], v[136:137]
	v_pk_mul_f32 v[144:145], v[138:139], v[138:139]
	v_cvt_pk_bf16_f32 v136, v140, v141
	v_cvt_pk_bf16_f32 v137, v148, v149
	v_cvt_pk_bf16_f32 v138, v146, v147
	v_cvt_pk_bf16_f32 v139, v144, v145
	flat_store_dwordx4 v[142:143], v[136:139] offset:256
	v_pk_mul_f32 v[140:141], v[84:85], v[134:135] op_sel_hi:[1,0]
	v_pk_mul_f32 v[142:143], v[82:83], v[134:135] op_sel_hi:[1,0]
	v_pk_mul_f32 v[138:139], v[86:87], v[134:135] op_sel_hi:[1,0]
	v_pk_mul_f32 v[136:137], v[88:89], v[134:135] op_sel_hi:[1,0]
	v_max_f32_e32 v138, 0, v138
	v_max_f32_e32 v139, 0, v139
	v_max_f32_e32 v140, 0, v140
	v_max_f32_e32 v141, 0, v141
	v_max_f32_e32 v142, 0, v142
	v_pk_mul_f32 v[138:139], v[138:139], v[138:139]
	v_max_f32_e32 v143, 0, v143
	v_max_f32_e32 v136, 0, v136
	v_max_f32_e32 v137, 0, v137
; __device__ __forceinline__ unsigned pk2(float lo, float hi) { const f32x2_t f = {lo, hi}; const bf16x2_t b = __builtin_convertvector(f, bf16x2_t); return __builtin_bit_cast(unsigned, b); }
;   __device__ __forceinline__ void operator()(const f32x4 (&acc)[2][2][4][2], const pg8::Unit& u, int wr, int wc, int fr, int fq) const {
;     ...
; #pragma unroll
;       for (int ai = 0; ai < 2; ++ai)
; #pragma unroll
;         for (int m = 0; m < 4; ++m) {
;           const int row = row0 + ai * 128 + m * 16; const float rs = rsv[ai][m];
; #pragma unroll
;           for (int bj = 0; bj < 2; ++bj) {
;             const int c = col0 + bj * 128;
;             f32x4 a = acc[ai][bj][m][0] * rs, b = acc[ai][bj][m][1] * rs;
; #pragma unroll
;             for (int e = 0; e < 4; ++e) { a[e] = fmaxf(a[e], 0.f); a[e] *= a[e]; b[e] = fmaxf(b[e], 0.f); b[e] *= b[e]; }
;             u32x4 o; o.x = pk2(a[0], a[1]); o.y = pk2(a[2], a[3]); o.z = pk2(b[0], b[1]); o.w = pk2(b[2], b[3]);
;             *(u32x4*)(hb + (size_t)row * DFF + c) = o;
;           }
;         }
	v_pk_mul_f32 v[140:141], v[140:141], v[140:141]
	v_pk_mul_f32 v[142:143], v[142:143], v[142:143]
	v_pk_mul_f32 v[144:145], v[136:137], v[136:137]
	v_cvt_pk_bf16_f32 v136, v138, v139
	v_cvt_pk_bf16_f32 v139, v140, v141
	v_lshl_add_u64 v[140:141], v[130:131], 0, s[10:11]
	s_mov_b32 s10, 0x120000
	v_cvt_pk_bf16_f32 v138, v142, v143
	v_add_co_u32_e32 v142, vcc, s10, v130
	v_cvt_pk_bf16_f32 v137, v144, v145
	s_nop 0
	v_addc_co_u32_e32 v143, vcc, 0, v131, vcc
	flat_store_dwordx4 v[142:143], v[136:139]
	v_pk_mul_f32 v[142:143], v[18:19], v[134:135] op_sel_hi:[1,0]
	s_mov_b64 s[10:11], 0x140000
	v_pk_mul_f32 v[136:137], v[22:23], v[134:135] op_sel_hi:[1,0]
	v_pk_mul_f32 v[138:139], v[20:21], v[134:135] op_sel_hi:[1,0]
	v_pk_mul_f32 v[134:135], v[16:17], v[134:135] op_sel_hi:[1,0]
	v_max_f32_e32 v138, 0, v138
	v_max_f32_e32 v134, 0, v134
	v_max_f32_e32 v135, 0, v135
	v_max_f32_e32 v139, 0, v139
	v_pk_mul_f32 v[144:145], v[134:135], v[134:135]
	v_max_f32_e32 v134, 0, v136
	v_max_f32_e32 v136, 0, v142
	v_max_f32_e32 v135, 0, v137
	v_max_f32_e32 v137, 0, v143
	v_pk_mul_f32 v[138:139], v[138:139], v[138:139]
	v_pk_mul_f32 v[146:147], v[134:135], v[134:135]
	v_pk_mul_f32 v[142:143], v[136:137], v[136:137]
	v_cvt_pk_bf16_f32 v134, v138, v139
	v_cvt_pk_bf16_f32 v135, v146, v147
	v_cvt_pk_bf16_f32 v136, v144, v145
	v_cvt_pk_bf16_f32 v137, v142, v143
	flat_store_dwordx4 v[140:141], v[134:137] offset:256
	v_pk_mul_f32 v[138:139], v[74:75], v[132:133] op_sel_hi:[1,0]
	v_pk_mul_f32 v[140:141], v[72:73], v[132:133] op_sel_hi:[1,0]
	v_pk_mul_f32 v[136:137], v[76:77], v[132:133] op_sel_hi:[1,0]
	v_pk_mul_f32 v[134:135], v[78:79], v[132:133] op_sel_hi:[1,0]
	v_max_f32_e32 v136, 0, v136
	v_max_f32_e32 v137, 0, v137
	v_max_f32_e32 v138, 0, v138
	v_max_f32_e32 v139, 0, v139
	v_max_f32_e32 v140, 0, v140
	v_pk_mul_f32 v[136:137], v[136:137], v[136:137]
	v_max_f32_e32 v141, 0, v141
	v_max_f32_e32 v134, 0, v134
	v_max_f32_e32 v135, 0, v135
	v_pk_mul_f32 v[138:139], v[138:139], v[138:139]
	v_pk_mul_f32 v[140:141], v[140:141], v[140:141]
	v_pk_mul_f32 v[142:143], v[134:135], v[134:135]
	v_cvt_pk_bf16_f32 v134, v136, v137
	v_cvt_pk_bf16_f32 v137, v138, v139
	v_lshl_add_u64 v[138:139], v[130:131], 0, s[10:11]
	s_mov_b32 s10, 0x140000
	v_cvt_pk_bf16_f32 v136, v140, v141
	v_add_co_u32_e32 v140, vcc, s10, v130
	v_cvt_pk_bf16_f32 v135, v142, v143
	s_nop 0
	v_addc_co_u32_e32 v141, vcc, 0, v131, vcc
	flat_store_dwordx4 v[140:141], v[134:137]
	v_pk_mul_f32 v[140:141], v[10:11], v[132:133] op_sel_hi:[1,0]
	s_mov_b64 s[10:11], 0x160000
	v_pk_mul_f32 v[134:135], v[14:15], v[132:133] op_sel_hi:[1,0]
	v_pk_mul_f32 v[136:137], v[12:13], v[132:133] op_sel_hi:[1,0]
	v_pk_mul_f32 v[132:133], v[8:9], v[132:133] op_sel_hi:[1,0]
	v_max_f32_e32 v136, 0, v136
	v_max_f32_e32 v132, 0, v132
	v_max_f32_e32 v133, 0, v133
	v_max_f32_e32 v137, 0, v137
	v_pk_mul_f32 v[142:143], v[132:133], v[132:133]
	v_max_f32_e32 v132, 0, v134
	v_max_f32_e32 v134, 0, v140
	v_max_f32_e32 v133, 0, v135
	v_max_f32_e32 v135, 0, v141
	v_pk_mul_f32 v[136:137], v[136:137], v[136:137]
	v_pk_mul_f32 v[144:145], v[132:133], v[132:133]
	v_pk_mul_f32 v[140:141], v[134:135], v[134:135]
	v_cvt_pk_bf16_f32 v132, v136, v137
	v_cvt_pk_bf16_f32 v133, v144, v145
	v_cvt_pk_bf16_f32 v134, v142, v143
	v_cvt_pk_bf16_f32 v135, v140, v141
	flat_store_dwordx4 v[138:139], v[132:135] offset:256
	v_pk_mul_f32 v[136:137], v[66:67], v[80:81] op_sel_hi:[1,0]
	v_pk_mul_f32 v[138:139], v[64:65], v[80:81] op_sel_hi:[1,0]
	v_pk_mul_f32 v[134:135], v[68:69], v[80:81] op_sel_hi:[1,0]
	v_pk_mul_f32 v[132:133], v[70:71], v[80:81] op_sel_hi:[1,0]
	v_max_f32_e32 v134, 0, v134
	v_max_f32_e32 v135, 0, v135
	v_max_f32_e32 v136, 0, v136
	v_max_f32_e32 v137, 0, v137
	v_pk_mul_f32 v[134:135], v[134:135], v[134:135]
	v_max_f32_e32 v132, 0, v132
	v_max_f32_e32 v133, 0, v133
	v_pk_mul_f32 v[136:137], v[136:137], v[136:137]
	v_max_f32_e32 v138, 0, v138
	v_max_f32_e32 v139, 0, v139
	v_pk_mul_f32 v[140:141], v[132:133], v[132:133]
	v_cvt_pk_bf16_f32 v132, v134, v135
	v_cvt_pk_bf16_f32 v135, v136, v137
	v_lshl_add_u64 v[136:137], v[130:131], 0, s[10:11]
	s_mov_b32 s10, 0x160000
	v_pk_mul_f32 v[138:139], v[138:139], v[138:139]
	v_add_co_u32_e32 v130, vcc, s10, v130
	v_cvt_pk_bf16_f32 v133, v140, v141
	v_cvt_pk_bf16_f32 v134, v138, v139
	v_addc_co_u32_e32 v131, vcc, 0, v131, vcc
	flat_store_dwordx4 v[130:131], v[132:135]
	v_pk_mul_f32 v[130:131], v[6:7], v[80:81] op_sel_hi:[1,0]
	v_pk_mul_f32 v[138:139], v[0:1], v[80:81] op_sel_hi:[1,0]
	v_pk_mul_f32 v[132:133], v[4:5], v[80:81] op_sel_hi:[1,0]
	v_pk_mul_f32 v[134:135], v[2:3], v[80:81] op_sel_hi:[1,0]
	v_max_f32_e32 v132, 0, v132
	v_max_f32_e32 v138, 0, v138
	v_max_f32_e32 v133, 0, v133
	v_max_f32_e32 v139, 0, v139
	v_max_f32_e32 v130, 0, v130
	v_max_f32_e32 v134, 0, v134
	v_max_f32_e32 v131, 0, v131
	v_max_f32_e32 v135, 0, v135
	v_pk_mul_f32 v[132:133], v[132:133], v[132:133]
	v_pk_mul_f32 v[138:139], v[138:139], v[138:139]
	v_pk_mul_f32 v[140:141], v[130:131], v[130:131]
	v_pk_mul_f32 v[134:135], v[134:135], v[134:135]
	v_cvt_pk_bf16_f32 v130, v132, v133
	v_cvt_pk_bf16_f32 v131, v140, v141
	v_cvt_pk_bf16_f32 v132, v138, v139
	v_cvt_pk_bf16_f32 v133, v134, v135
	flat_store_dwordx4 v[136:137], v[130:133] offset:256

; __device__ __forceinline__ unsigned pk2(float lo, float hi) { const f32x2_t f = {lo, hi}; const bf16x2_t b = __builtin_convertvector(f, bf16x2_t); return __builtin_bit_cast(unsigned, b); }
;   __device__ __forceinline__ void operator()(const f32x4 (&acc)[2][2][4][2], const pg8::Unit& u, int wr, int wc, int fr, int fq) const {
;     ...
;       const float* rstd1 = (const float*)(ws + O_RSTD1) + (size_t)slice * TS;
;       if (u.swap) {
;         u16* hyT = (u16*)(ws + O_HYT);
;         f32x4 rr[2][2];
; #pragma unroll
;         for (int bj = 0; bj < 2; ++bj) { rr[bj][0] = *(const f32x4*)(rstd1 + col0 + bj * 128); rr[bj][1] = *(const f32x4*)(rstd1 + col0 + bj * 128 + 4); }
;         __builtin_amdgcn_sched_barrier(0);
; #pragma unroll
;         for (int bj = 0; bj < 2; ++bj) {
;           const int tok0 = col0 + bj * 128;
; #pragma unroll
;           for (int ai = 0; ai < 2; ++ai)
; #pragma unroll
;             for (int m = 0; m < 4; ++m) {
;               const int ch = row0 + ai * 128 + m * 16 - 4608;
;               const f32x4 a = acc[ai][bj][m][0] * rr[bj][0], b = acc[ai][bj][m][1] * rr[bj][1];
;               u32x4 o; o.x = pk2(a[0], a[1]); o.y = pk2(a[2], a[3]); o.z = pk2(b[0], b[1]); o.w = pk2(b[2], b[3]);
;               *(u32x4*)(hyT + (size_t)ch * TS + tok0) = o;
;             }
;         }
.LBB0_151:
	s_andn2_b64 vcc, exec, s[10:11]
	s_cbranch_vccnz .LBB0_50
	s_cmp_gt_i32 s98, 0
	s_mov_b64 s[10:11], -1
	s_cbranch_scc0 .LBB0_285
	s_andn2_b64 vcc, exec, s[0:1]
	v_ashrrev_i32_e32 v175, 31, v174
	s_cbranch_vccnz .LBB0_155
	v_lshl_add_u64 v[130:131], v[174:175], 2, s[82:83]
	v_mov_b64_e32 v[138:139], v[238:239]
	v_mov_b64_e32 v[140:141], v[240:241]
	v_mov_b64_e32 v[142:143], v[244:245]
	v_mov_b64_e32 v[144:145], v[246:247]
	v_mov_b64_e32 v[134:135], v[248:249]
	v_mov_b64_e32 v[136:137], v[250:251]
	s_nop 0
	v_mov_b64_e32 v[130:131], v[230:231]
	v_mov_b64_e32 v[132:133], v[234:235]
	v_add_u32_e32 v150, 0xffffee00, v176
	v_readlane_b32 s0, v254, 30
	v_readlane_b32 s1, v254, 31
	v_ashrrev_i32_e32 v151, 31, v150
	v_pk_mul_f32 v[148:149], v[128:129], v[140:141]
	v_lshl_add_u64 v[152:153], v[174:175], 1, s[0:1]
	v_pk_mul_f32 v[146:147], v[126:127], v[138:139]
	v_pk_mul_f32 v[154:155], v[124:125], v[144:145]
	v_pk_mul_f32 v[156:157], v[122:123], v[142:143]
	v_lshlrev_b64 v[150:151], 15, v[150:151]
	v_cvt_pk_bf16_f32 v146, v146, v147
	v_cvt_pk_bf16_f32 v147, v148, v149
	v_cvt_pk_bf16_f32 v148, v156, v157
	v_cvt_pk_bf16_f32 v149, v154, v155
	v_lshl_add_u64 v[150:151], v[152:153], 0, v[150:151]
	v_add_u32_e32 v154, 0xffffee10, v176
	flat_store_dwordx4 v[150:151], v[146:149]
	v_pk_mul_f32 v[156:157], v[116:117], v[144:145]
	v_ashrrev_i32_e32 v155, 31, v154
	v_pk_mul_f32 v[148:149], v[120:121], v[140:141]
	v_pk_mul_f32 v[146:147], v[118:119], v[138:139]
	v_pk_mul_f32 v[158:159], v[114:115], v[142:143]
	v_cvt_pk_bf16_f32 v146, v146, v147
	v_cvt_pk_bf16_f32 v147, v148, v149
	v_cvt_pk_bf16_f32 v149, v156, v157
	v_lshlrev_b64 v[154:155], 15, v[154:155]
	v_add_u32_e32 v156, 0xffffee20, v176
	v_cvt_pk_bf16_f32 v148, v158, v159
	v_lshl_add_u64 v[154:155], v[152:153], 0, v[154:155]
	v_ashrrev_i32_e32 v157, 31, v156
	flat_store_dwordx4 v[154:155], v[146:149]
	v_pk_mul_f32 v[158:159], v[108:109], v[144:145]
	v_pk_mul_f32 v[160:161], v[106:107], v[142:143]
	v_pk_mul_f32 v[148:149], v[112:113], v[140:141]
	v_pk_mul_f32 v[146:147], v[110:111], v[138:139]
	v_lshlrev_b64 v[156:157], 15, v[156:157]
	v_cvt_pk_bf16_f32 v146, v146, v147
	v_cvt_pk_bf16_f32 v147, v148, v149
	v_cvt_pk_bf16_f32 v148, v160, v161
	v_cvt_pk_bf16_f32 v149, v158, v159
	v_lshl_add_u64 v[156:157], v[152:153], 0, v[156:157]
	v_add_u32_e32 v158, 0xffffee30, v176
	flat_store_dwordx4 v[156:157], v[146:149]
	v_pk_mul_f32 v[160:161], v[100:101], v[144:145]
	v_ashrrev_i32_e32 v159, 31, v158
	v_pk_mul_f32 v[148:149], v[104:105], v[140:141]
	v_pk_mul_f32 v[146:147], v[102:103], v[138:139]
	v_pk_mul_f32 v[178:179], v[98:99], v[142:143]
	v_cvt_pk_bf16_f32 v146, v146, v147
	v_cvt_pk_bf16_f32 v147, v148, v149
	v_cvt_pk_bf16_f32 v149, v160, v161
	v_lshlrev_b64 v[158:159], 15, v[158:159]
	v_add_u32_e32 v160, 0xffffee80, v176
	v_cvt_pk_bf16_f32 v148, v178, v179
	v_lshl_add_u64 v[158:159], v[152:153], 0, v[158:159]
	v_ashrrev_i32_e32 v161, 31, v160
	flat_store_dwordx4 v[158:159], v[146:149]
	v_pk_mul_f32 v[178:179], v[92:93], v[144:145]
	v_pk_mul_f32 v[180:181], v[90:91], v[142:143]
	v_pk_mul_f32 v[148:149], v[96:97], v[140:141]
	v_pk_mul_f32 v[146:147], v[94:95], v[138:139]
	v_lshlrev_b64 v[160:161], 15, v[160:161]
	v_cvt_pk_bf16_f32 v146, v146, v147
	v_cvt_pk_bf16_f32 v147, v148, v149
	v_cvt_pk_bf16_f32 v148, v180, v181
	v_cvt_pk_bf16_f32 v149, v178, v179
	v_lshl_add_u64 v[160:161], v[152:153], 0, v[160:161]
	v_add_u32_e32 v178, 0xffffee90, v176
	flat_store_dwordx4 v[160:161], v[146:149]
	v_pk_mul_f32 v[180:181], v[84:85], v[144:145]
	v_ashrrev_i32_e32 v179, 31, v178
	v_pk_mul_f32 v[148:149], v[88:89], v[140:141]
	v_pk_mul_f32 v[146:147], v[86:87], v[138:139]
	v_pk_mul_f32 v[182:183], v[82:83], v[142:143]
	v_cvt_pk_bf16_f32 v146, v146, v147
	v_cvt_pk_bf16_f32 v147, v148, v149
	v_cvt_pk_bf16_f32 v149, v180, v181
	v_lshlrev_b64 v[178:179], 15, v[178:179]
	v_add_u32_e32 v180, 0xffffeea0, v176
	v_cvt_pk_bf16_f32 v148, v182, v183
	v_lshl_add_u64 v[178:179], v[152:153], 0, v[178:179]
	v_ashrrev_i32_e32 v181, 31, v180
	flat_store_dwordx4 v[178:179], v[146:149]
	v_pk_mul_f32 v[182:183], v[74:75], v[144:145]
	v_pk_mul_f32 v[184:185], v[72:73], v[142:143]
	v_pk_mul_f32 v[148:149], v[78:79], v[140:141]
	v_pk_mul_f32 v[146:147], v[76:77], v[138:139]
	v_lshlrev_b64 v[180:181], 15, v[180:181]
	v_cvt_pk_bf16_f32 v146, v146, v147
	v_cvt_pk_bf16_f32 v147, v148, v149
	v_cvt_pk_bf16_f32 v148, v184, v185
	v_cvt_pk_bf16_f32 v149, v182, v183
	v_lshl_add_u64 v[180:181], v[152:153], 0, v[180:181]
; __device__ __forceinline__ unsigned pk2(float lo, float hi) { const f32x2_t f = {lo, hi}; const bf16x2_t b = __builtin_convertvector(f, bf16x2_t); return __builtin_bit_cast(unsigned, b); }
;   __device__ __forceinline__ void operator()(const f32x4 (&acc)[2][2][4][2], const pg8::Unit& u, int wr, int wc, int fr, int fq) const {
;     ...
;         for (int bj = 0; bj < 2; ++bj) {
;           const int tok0 = col0 + bj * 128;
; #pragma unroll
;           for (int ai = 0; ai < 2; ++ai)
; #pragma unroll
;             for (int m = 0; m < 4; ++m) {
;               const int ch = row0 + ai * 128 + m * 16 - 4608;
;               const f32x4 a = acc[ai][bj][m][0] * rr[bj][0], b = acc[ai][bj][m][1] * rr[bj][1];
;               u32x4 o; o.x = pk2(a[0], a[1]); o.y = pk2(a[2], a[3]); o.z = pk2(b[0], b[1]); o.w = pk2(b[2], b[3]);
;               *(u32x4*)(hyT + (size_t)ch * TS + tok0) = o;
;             }
;     ...
;         float rsv[2][4];
; #pragma unroll
;         for (int ai = 0; ai < 2; ++ai)
; #pragma unroll
;           for (int m = 0; m < 4; ++m) rsv[ai][m] = rstd1[row0 + ai * 128 + m * 16];
;         __builtin_amdgcn_sched_barrier(0);
; #pragma unroll
;         for (int ai = 0; ai < 2; ++ai)
; #pragma unroll
;           for (int m = 0; m < 4; ++m) {
;             const int row = row0 + ai * 128 + m * 16; const float rs = rsv[ai][m];
; #pragma unroll
;             for (int bj = 0; bj < 2; ++bj) {
;               const int c = col0 + bj * 128;
;               f32x4 a = acc[ai][bj][m][0] * rs, b = acc[ai][bj][m][1] * rs;
;               if (isg) {
; #pragma unroll
;                 for (int e = 0; e < 4; ++e) { a[e] = __builtin_amdgcn_rcpf(1.0f + __expf(-a[e])); b[e] = __builtin_amdgcn_rcpf(1.0f + __expf(-b[e])); }
;               }
;               u32x4 o; o.x = pk2(a[0], a[1]); o.y = pk2(a[2], a[3]); o.z = pk2(b[0], b[1]); o.w = pk2(b[2], b[3]);
;               if (isg) *(u32x4*)(sg + (size_t)row * 2048 + (c - 7680)) = o; else *(u32x4*)(qkv + (size_t)row * 4608 + c) = o;
	flat_store_dwordx4 v[180:181], v[146:149]
	v_pk_mul_f32 v[140:141], v[70:71], v[140:141]
	v_pk_mul_f32 v[138:139], v[68:69], v[138:139]
	v_add_u32_e32 v146, 0xffffeeb0, v176
	v_pk_mul_f32 v[142:143], v[64:65], v[142:143]
	v_ashrrev_i32_e32 v147, 31, v146
	v_pk_mul_f32 v[144:145], v[66:67], v[144:145]
	v_cvt_pk_bf16_f32 v138, v138, v139
	v_cvt_pk_bf16_f32 v139, v140, v141
	v_cvt_pk_bf16_f32 v140, v142, v143
	v_lshlrev_b64 v[142:143], 15, v[146:147]
	v_cvt_pk_bf16_f32 v141, v144, v145
	v_lshl_add_u64 v[142:143], v[152:153], 0, v[142:143]
	flat_store_dwordx4 v[142:143], v[138:141]
	v_pk_mul_f32 v[144:145], v[58:59], v[132:133]
	v_pk_mul_f32 v[146:147], v[56:57], v[130:131]
	v_pk_mul_f32 v[140:141], v[62:63], v[136:137]
	v_pk_mul_f32 v[138:139], v[60:61], v[134:135]
	s_mov_b64 s[10:11], 0
	v_cvt_pk_bf16_f32 v138, v138, v139
	v_cvt_pk_bf16_f32 v139, v140, v141
	v_cvt_pk_bf16_f32 v140, v146, v147
	v_cvt_pk_bf16_f32 v141, v144, v145
	flat_store_dwordx4 v[150:151], v[138:141] offset:256
	v_pk_mul_f32 v[144:145], v[50:51], v[132:133]
	v_pk_mul_f32 v[146:147], v[48:49], v[130:131]
	v_pk_mul_f32 v[140:141], v[54:55], v[136:137]
	v_pk_mul_f32 v[138:139], v[52:53], v[134:135]
	s_nop 0
	v_cvt_pk_bf16_f32 v138, v138, v139
	v_cvt_pk_bf16_f32 v139, v140, v141
	v_cvt_pk_bf16_f32 v140, v146, v147
	v_cvt_pk_bf16_f32 v141, v144, v145
	flat_store_dwordx4 v[154:155], v[138:141] offset:256
	v_pk_mul_f32 v[144:145], v[42:43], v[132:133]
	v_pk_mul_f32 v[146:147], v[40:41], v[130:131]
	v_pk_mul_f32 v[140:141], v[46:47], v[136:137]
	v_pk_mul_f32 v[138:139], v[44:45], v[134:135]
	s_nop 0
	v_cvt_pk_bf16_f32 v138, v138, v139
	v_cvt_pk_bf16_f32 v139, v140, v141
	v_cvt_pk_bf16_f32 v140, v146, v147
	v_cvt_pk_bf16_f32 v141, v144, v145
	flat_store_dwordx4 v[156:157], v[138:141] offset:256
	v_pk_mul_f32 v[144:145], v[34:35], v[132:133]
	v_pk_mul_f32 v[146:147], v[32:33], v[130:131]
	v_pk_mul_f32 v[140:141], v[38:39], v[136:137]
	v_pk_mul_f32 v[138:139], v[36:37], v[134:135]
	s_nop 0
	v_cvt_pk_bf16_f32 v138, v138, v139
	v_cvt_pk_bf16_f32 v139, v140, v141
	v_cvt_pk_bf16_f32 v140, v146, v147
	v_cvt_pk_bf16_f32 v141, v144, v145
	flat_store_dwordx4 v[158:159], v[138:141] offset:256
	v_pk_mul_f32 v[144:145], v[26:27], v[132:133]
	v_pk_mul_f32 v[146:147], v[24:25], v[130:131]
	v_pk_mul_f32 v[140:141], v[30:31], v[136:137]
	v_pk_mul_f32 v[138:139], v[28:29], v[134:135]
	s_nop 0
	v_cvt_pk_bf16_f32 v138, v138, v139
	v_cvt_pk_bf16_f32 v139, v140, v141
	v_cvt_pk_bf16_f32 v140, v146, v147
	v_cvt_pk_bf16_f32 v141, v144, v145
	flat_store_dwordx4 v[160:161], v[138:141] offset:256
	v_pk_mul_f32 v[144:145], v[18:19], v[132:133]
	v_pk_mul_f32 v[146:147], v[16:17], v[130:131]
	v_pk_mul_f32 v[140:141], v[22:23], v[136:137]
	v_pk_mul_f32 v[138:139], v[20:21], v[134:135]
	s_nop 0
	v_cvt_pk_bf16_f32 v138, v138, v139
	v_cvt_pk_bf16_f32 v139, v140, v141
	v_cvt_pk_bf16_f32 v140, v146, v147
	v_cvt_pk_bf16_f32 v141, v144, v145
	flat_store_dwordx4 v[178:179], v[138:141] offset:256
	v_pk_mul_f32 v[144:145], v[10:11], v[132:133]
	v_pk_mul_f32 v[146:147], v[8:9], v[130:131]
	v_pk_mul_f32 v[140:141], v[14:15], v[136:137]
	v_pk_mul_f32 v[138:139], v[12:13], v[134:135]
	v_pk_mul_f32 v[136:137], v[6:7], v[136:137]
	v_cvt_pk_bf16_f32 v138, v138, v139
	v_cvt_pk_bf16_f32 v139, v140, v141
	v_cvt_pk_bf16_f32 v140, v146, v147
	v_cvt_pk_bf16_f32 v141, v144, v145
	flat_store_dwordx4 v[180:181], v[138:141] offset:256
	v_pk_mul_f32 v[134:135], v[4:5], v[134:135]
	s_nop 0
	v_pk_mul_f32 v[138:139], v[2:3], v[132:133]
	v_pk_mul_f32 v[132:133], v[0:1], v[130:131]
	v_cvt_pk_bf16_f32 v130, v134, v135
	v_cvt_pk_bf16_f32 v131, v136, v137
	v_cvt_pk_bf16_f32 v132, v132, v133
	v_cvt_pk_bf16_f32 v133, v138, v139
	flat_store_dwordx4 v[142:143], v[130:133] offset:256
.LBB0_155:
	s_andn2_b64 vcc, exec, s[10:11]
	s_cbranch_vccnz .LBB0_284
	v_ashrrev_i32_e32 v177, 31, v176
	v_lshl_add_u64 v[130:131], v[176:177], 2, s[82:83]
	v_mov_b32_e32 v148, v238
	v_mov_b32_e32 v146, v239
	v_mov_b32_e32 v144, v240
	v_mov_b32_e32 v142, v241
	v_mov_b32_e32 v140, v244
	v_mov_b32_e32 v138, v245
	v_mov_b32_e32 v136, v246
	v_mov_b32_e32 v134, v247
	s_cmp_lt_i32 s72, 30
	s_cselect_b64 s[0:1], -1, 0
	s_cmp_gt_i32 s72, 29
	v_pk_mul_f32 v[132:133], v[128:129], v[148:149] op_sel_hi:[1,0]
	v_pk_mul_f32 v[130:131], v[126:127], v[148:149] op_sel_hi:[1,0]
	v_pk_mul_f32 v[150:151], v[124:125], v[148:149] op_sel_hi:[1,0]
	v_pk_mul_f32 v[152:153], v[122:123], v[148:149] op_sel_hi:[1,0]
	s_mov_b64 s[10:11], -1
	s_cbranch_scc1 .LBB0_158
	s_mov_b64 s[10:11], 0
